# v65: last XCD leader bumps every XCD's release word directly (no leader relay)
# speedup vs baseline: 1.0099x; 1.0099x over previous
.LBB0_140:
	s_or_b64 exec, exec, s[6:7]
	s_and_saveexec_b64 s[6:7], s[10:11]
	s_cbranch_execz .LBB0_142
	v_mov_b32_e32 v1, 1
	global_atomic_add v[2:3], v1, off
	v_readlane_b32 s98, v254, 41
	v_readlane_b32 s99, v254, 42
	v_mov_b32_e32 v252, 0x2400
	s_nop 5
	global_atomic_add v252, v1, s[98:99]
	global_atomic_add v252, v1, s[98:99] offset:256
	global_atomic_add v252, v1, s[98:99] offset:512
	global_atomic_add v252, v1, s[98:99] offset:768
	global_atomic_add v252, v1, s[98:99] offset:1024
	global_atomic_add v252, v1, s[98:99] offset:1280
	global_atomic_add v252, v1, s[98:99] offset:1536
	global_atomic_add v252, v1, s[98:99] offset:1792
	global_atomic_add v252, v1, s[98:99] offset:2048
	global_atomic_add v252, v1, s[98:99] offset:2304
	global_atomic_add v252, v1, s[98:99] offset:2560
	global_atomic_add v252, v1, s[98:99] offset:2816
	global_atomic_add v252, v1, s[98:99] offset:3072
	global_atomic_add v252, v1, s[98:99] offset:3328
	global_atomic_add v252, v1, s[98:99] offset:3584
	global_atomic_add v252, v1, s[98:99] offset:3840
.LBB0_142:
	s_or_b64 exec, exec, s[6:7]
	s_mov_b64 s[6:7], exec
	v_mbcnt_lo_u32_b32 v1, s6, 0
	v_mbcnt_hi_u32_b32 v1, s7, v1
	v_cmp_eq_u32_e32 vcc, 0, v1
	s_waitcnt vmcnt(0)
	s_and_saveexec_b64 s[8:9], vcc
	s_cbranch_execz .LBB0_144
	s_bcnt1_i32_b64 s6, s[6:7]
	v_mov_b32_e32 v1, 0x2000
	v_mov_b32_e32 v2, s6

.LBB0_623:
	s_or_b64 exec, exec, s[4:5]
	s_and_saveexec_b64 s[4:5], s[8:9]
	s_cbranch_execz .LBB0_625
	v_mov_b32_e32 v1, 1
	global_atomic_add v[2:3], v1, off
	v_readlane_b32 s98, v254, 41
	v_readlane_b32 s99, v254, 42
	v_mov_b32_e32 v252, 0x2400
	s_nop 5
	global_atomic_add v252, v1, s[98:99]
	global_atomic_add v252, v1, s[98:99] offset:256
	global_atomic_add v252, v1, s[98:99] offset:512
	global_atomic_add v252, v1, s[98:99] offset:768
	global_atomic_add v252, v1, s[98:99] offset:1024
	global_atomic_add v252, v1, s[98:99] offset:1280
	global_atomic_add v252, v1, s[98:99] offset:1536
	global_atomic_add v252, v1, s[98:99] offset:1792
	global_atomic_add v252, v1, s[98:99] offset:2048
	global_atomic_add v252, v1, s[98:99] offset:2304
	global_atomic_add v252, v1, s[98:99] offset:2560
	global_atomic_add v252, v1, s[98:99] offset:2816
	global_atomic_add v252, v1, s[98:99] offset:3072
	global_atomic_add v252, v1, s[98:99] offset:3328
	global_atomic_add v252, v1, s[98:99] offset:3584
	global_atomic_add v252, v1, s[98:99] offset:3840
.LBB0_625:
	s_or_b64 exec, exec, s[4:5]
	s_mov_b64 s[4:5], exec
	v_mbcnt_lo_u32_b32 v1, s4, 0
	v_mbcnt_hi_u32_b32 v1, s5, v1
	v_cmp_eq_u32_e32 vcc, 0, v1
	s_waitcnt vmcnt(0)
	s_and_saveexec_b64 s[6:7], vcc
	s_cbranch_execz .LBB0_627
	s_bcnt1_i32_b64 s4, s[4:5]
	v_mov_b32_e32 v1, 0x2000
	v_mov_b32_e32 v2, s4
